# prep transposes: 4 row loads per 32x32 tile issued back to back with counted waits (was 3-4 serialized HBM round trips)
# speedup vs baseline: 1.0181x; 1.0055x over previous
; DEV int tidx() { int t = threadIdx.x; asm volatile("" : "+v"(t)); return t; }
; DEV void transpose_tile(const float* __restrict__ W, int K, int N, bf16_t* __restrict__ Wt, int ldt, int tile, char* smem) {
;   float* sm = (float*)smem;
;   const int ntn = N >> 5;
;   const int kt = tile / ntn, nt = tile - kt * ntn;
;   const int tx = tidx() & 31, ty = tidx() >> 5;
;   __syncthreads();
; #pragma unroll
;   for (int i = 0; i < 4; i++) { int k = ty + i * 8; sm[k * 33 + tx] = W[(size_t)(kt * 32 + k) * N + nt * 32 + tx]; }
;   __syncthreads();
; #pragma unroll
;   for (int i = 0; i < 4; i++) { int n = ty + i * 8; Wt[(size_t)(nt * 32 + n) * ldt + kt * 32 + tx] = f2bf(sm[tx * 33 + n]); }
; }
; DEV void phase_prep(const Params& p, char* smem) {
;     ...
;       if (it < NT_WOUT) { transpose_tile(p.in[I_WOUT], 1024, 1024, WSP(bf16_t, S_WOUT0), LDH, it, smem); continue; }
;       it -= NT_WOUT;
;       if (it < NT_HGIN) { transpose_tile(p.in[I_HGWIN], 1024, 5120, WSP(bf16_t, S_WHGIN), LDH, it, smem); continue; }
;       it -= NT_HGIN;
;       if (it < NT_HGOUT) { transpose_tile(p.in[I_HGWOUT], 1024, 1024, WSP(bf16_t, S_WHGOUT), LDH, it, smem); continue; }
;       it -= NT_HGOUT;
;       int l = it >> 11; it &= 2047;
;       transpose_tile(p.in[I_PWQ] + (size_t)l * 1024 * 2048, 1024, 2048, WSP(bf16_t, S_WPQ) + (size_t)l * 2048 * LDH, LDH, it, smem);
.LBB0_1110:
	s_andn2_b64 vcc, exec, s[12:13]
	s_cbranch_vccnz .LBB0_1065
	s_cmpk_gt_i32 s49, 0x59f
	s_mov_b64 s[12:13], -1
	s_cbranch_scc0 .LBB0_1133
	s_cmpk_gt_u32 s49, 0x65f
	s_cbranch_scc0 .LBB0_1130
	s_cmpk_gt_u32 s49, 0x6df
	s_cbranch_scc0 .LBB0_1127
	s_cmpk_gt_u32 s49, 0xadf
	s_cbranch_scc0 .LBB0_1124
	s_cmpk_gt_u32 s49, 0x1edf
	s_cbranch_scc0 .LBB0_1121
	s_cmpk_gt_u32 s49, 0x22df
	s_cbranch_scc0 .LBB0_1118
	s_add_i32 s16, s49, 0xffffdd20
	s_lshr_b32 s52, s16, 11
	s_lshl_b64 s[12:13], s[52:53], 23
	v_readlane_b32 s17, v253, 55
	s_add_u32 s12, s17, s12
	v_readlane_b32 s17, v253, 56
	s_addc_u32 s13, s17, s13
	s_mul_i32 s38, s52, 0x440000
	s_mul_hi_u32 s17, s52, 0x440000
	s_add_u32 s38, s44, s38
	v_mov_b32_e32 v0, v195
	s_addc_u32 s17, s45, s17
	s_lshr_b32 s39, s16, 1
	s_lshl_b32 s16, s16, 5
	v_and_b32_e32 v8, 31, v0
	v_mov_b32_e32 v0, v195
	s_and_b32 s16, s16, 0x7e0
	s_and_b32 s39, s39, 0x3e0
	v_ashrrev_i32_e32 v9, 5, v0
	s_lshl_b32 s40, s16, 2
	s_add_u32 s12, s12, s40
	v_add_u32_e32 v4, s39, v9
	s_addc_u32 s13, s13, 0
	v_lshlrev_b32_e32 v0, 2, v8
	v_ashrrev_i32_e32 v5, 31, v4
	v_lshl_add_u64 v[2:3], s[12:13], 0, v[0:1]
	v_lshlrev_b64 v[4:5], 13, v[4:5]
	v_lshl_add_u64 v[4:5], v[2:3], 0, v[4:5]
	s_waitcnt lgkmcnt(0)
	s_barrier
	global_load_dword v80, v[4:5], off
	s_movk_i32 s12, 0x84
	v_mad_u64_u32 v[4:5], s[12:13], v9, s12, v[0:1]
	v_add_u32_e32 v10, 8, v9
	v_add_u32_e32 v11, 16, v9
	v_add_u32_e32 v12, 24, v9
	s_lshl_b32 s12, s39, 1
	s_add_u32 s12, s38, s12
	s_addc_u32 s13, s17, 0
	s_movk_i32 s17, 0x880
	v_add_u32_e32 v6, s39, v10
	v_ashrrev_i32_e32 v7, 31, v6
	v_lshlrev_b64 v[6:7], 13, v[6:7]
	v_lshl_add_u64 v[6:7], v[2:3], 0, v[6:7]
	global_load_dword v81, v[6:7], off
	v_add_u32_e32 v6, s39, v11
	v_ashrrev_i32_e32 v7, 31, v6
	v_lshlrev_b64 v[6:7], 13, v[6:7]
	v_lshl_add_u64 v[6:7], v[2:3], 0, v[6:7]
	global_load_dword v82, v[6:7], off
	v_add_u32_e32 v6, s39, v12
	v_ashrrev_i32_e32 v7, 31, v6
	v_lshlrev_b64 v[6:7], 13, v[6:7]
	v_lshl_add_u64 v[2:3], v[2:3], 0, v[6:7]
	global_load_dword v83, v[2:3], off
	s_waitcnt vmcnt(3)
	ds_write_b32 v4, v80
	s_waitcnt vmcnt(2)
	ds_write_b32 v4, v81 offset:1056
	s_waitcnt vmcnt(1)
	ds_write_b32 v4, v82 offset:2112
	s_waitcnt vmcnt(0)
	ds_write_b32 v4, v83 offset:3168
	v_add_u32_e32 v6, s16, v9
	v_lshl_or_b32 v4, v8, 7, v0
	v_lshlrev_b32_e32 v0, 1, v8
	v_lshl_add_u64 v[2:3], s[12:13], 0, v[0:1]
	v_lshl_add_u32 v0, v9, 2, v4
	s_waitcnt lgkmcnt(0)
	s_barrier
	ds_read2_b32 v[4:5], v0 offset1:8
	v_mad_i64_i32 v[6:7], s[12:13], v6, s17, v[2:3]
	s_waitcnt lgkmcnt(0)
	v_cvt_pk_bf16_f32 v4, v4, s0
	global_store_short v[6:7], v4, off
	v_add_u32_e32 v4, s16, v10
	v_cvt_pk_bf16_f32 v6, v5, s0
	v_mad_i64_i32 v[4:5], s[12:13], v4, s17, v[2:3]
	global_store_short v[4:5], v6, off
	ds_read2_b32 v[4:5], v0 offset0:16 offset1:24
	s_waitcnt lgkmcnt(0)
	v_cvt_pk_bf16_f32 v0, v4, s0
	v_add_u32_e32 v4, s16, v11
	v_mad_i64_i32 v[6:7], s[12:13], v4, s17, v[2:3]
	v_add_u32_e32 v4, s16, v12
	global_store_short v[6:7], v0, off
	v_cvt_pk_bf16_f32 v0, v5, s0
	v_mad_i64_i32 v[2:3], s[12:13], v4, s17, v[2:3]
	global_store_short v[2:3], v0, off
	s_mov_b64 s[12:13], 0
.LBB0_1118:
	s_andn2_b64 vcc, exec, s[12:13]
	s_cbranch_vccnz .LBB0_1120
	s_add_i32 s12, s49, 0xffffe120
	v_mov_b32_e32 v0, v195
	s_and_b32 s52, s12, 0xffffffe0
	s_lshl_b32 s12, s12, 5
	v_and_b32_e32 v8, 31, v0
	v_mov_b32_e32 v0, v195
	s_and_b32 s12, s12, 0x3e0
	s_lshl_b32 s13, s12, 2
	v_ashrrev_i32_e32 v9, 5, v0
	v_readlane_b32 s16, v253, 53
	s_add_u32 s16, s16, s13
	v_readlane_b32 s13, v253, 54
	v_add_u32_e32 v4, s52, v9
	s_addc_u32 s17, s13, 0
	v_lshlrev_b32_e32 v0, 2, v8
	v_ashrrev_i32_e32 v5, 31, v4
	v_lshl_add_u64 v[2:3], s[16:17], 0, v[0:1]
	v_lshlrev_b64 v[4:5], 12, v[4:5]
	v_lshl_add_u64 v[4:5], v[2:3], 0, v[4:5]
	s_waitcnt lgkmcnt(0)
	s_barrier
	global_load_dword v80, v[4:5], off
	s_movk_i32 s13, 0x84
	v_mad_u64_u32 v[4:5], s[16:17], v9, s13, v[0:1]
	v_add_u32_e32 v10, 8, v9
	v_add_u32_e32 v11, 16, v9
	v_add_u32_e32 v12, 24, v9
	s_lshl_b64 s[16:17], s[52:53], 1
	s_add_u32 s16, s22, s16
	s_addc_u32 s17, s23, s17
	s_movk_i32 s13, 0x880
	v_add_u32_e32 v6, s52, v10
	v_ashrrev_i32_e32 v7, 31, v6
	v_lshlrev_b64 v[6:7], 12, v[6:7]
	v_lshl_add_u64 v[6:7], v[2:3], 0, v[6:7]
	global_load_dword v81, v[6:7], off
	v_add_u32_e32 v6, s52, v11
	v_ashrrev_i32_e32 v7, 31, v6
	v_lshlrev_b64 v[6:7], 12, v[6:7]
	v_lshl_add_u64 v[6:7], v[2:3], 0, v[6:7]
	global_load_dword v82, v[6:7], off
	v_add_u32_e32 v6, s52, v12
	v_ashrrev_i32_e32 v7, 31, v6
	v_lshlrev_b64 v[6:7], 12, v[6:7]
	v_lshl_add_u64 v[2:3], v[2:3], 0, v[6:7]
	global_load_dword v83, v[2:3], off
	s_waitcnt vmcnt(3)
	ds_write_b32 v4, v80
	s_waitcnt vmcnt(2)
	ds_write_b32 v4, v81 offset:1056
	s_waitcnt vmcnt(1)
	ds_write_b32 v4, v82 offset:2112
	s_waitcnt vmcnt(0)
	ds_write_b32 v4, v83 offset:3168
	v_add_u32_e32 v6, s12, v9
	v_lshl_or_b32 v4, v8, 7, v0
	v_lshlrev_b32_e32 v0, 1, v8
	v_lshl_add_u64 v[2:3], s[16:17], 0, v[0:1]
	v_lshl_add_u32 v0, v9, 2, v4
	s_waitcnt lgkmcnt(0)
	s_barrier
	ds_read2_b32 v[4:5], v0 offset1:8
	v_mad_i64_i32 v[6:7], s[16:17], v6, s13, v[2:3]
	s_waitcnt lgkmcnt(0)
	v_cvt_pk_bf16_f32 v4, v4, s0
	global_store_short v[6:7], v4, off
	v_add_u32_e32 v4, s12, v10
	v_cvt_pk_bf16_f32 v6, v5, s0
	v_mad_i64_i32 v[4:5], s[16:17], v4, s13, v[2:3]
	global_store_short v[4:5], v6, off
	ds_read2_b32 v[4:5], v0 offset0:16 offset1:24
	s_waitcnt lgkmcnt(0)
	v_cvt_pk_bf16_f32 v0, v4, s0
	v_add_u32_e32 v4, s12, v11
	v_mad_i64_i32 v[6:7], s[16:17], v4, s13, v[2:3]
	v_add_u32_e32 v4, s12, v12
	global_store_short v[6:7], v0, off
	v_cvt_pk_bf16_f32 v0, v5, s0
	v_mad_i64_i32 v[2:3], s[12:13], v4, s13, v[2:3]
	global_store_short v[2:3], v0, off

; DEV int tidx() { int t = threadIdx.x; asm volatile("" : "+v"(t)); return t; }
; DEV void transpose_tile(const float* __restrict__ W, int K, int N, bf16_t* __restrict__ Wt, int ldt, int tile, char* smem) {
;   float* sm = (float*)smem;
;   const int ntn = N >> 5;
;   const int kt = tile / ntn, nt = tile - kt * ntn;
;   const int tx = tidx() & 31, ty = tidx() >> 5;
;   __syncthreads();
; #pragma unroll
;   for (int i = 0; i < 4; i++) { int k = ty + i * 8; sm[k * 33 + tx] = W[(size_t)(kt * 32 + k) * N + nt * 32 + tx]; }
;   __syncthreads();
; #pragma unroll
;   for (int i = 0; i < 4; i++) { int n = ty + i * 8; Wt[(size_t)(nt * 32 + n) * ldt + kt * 32 + tx] = f2bf(sm[tx * 33 + n]); }
; }
; DEV void phase_prep(const Params& p, char* smem) {
;     ...
;       if (it < NT_HGIN) { transpose_tile(p.in[I_HGWIN], 1024, 5120, WSP(bf16_t, S_WHGIN), LDH, it, smem); continue; }
.LBB0_1121:
	s_andn2_b64 vcc, exec, s[12:13]
	s_cbranch_vccnz .LBB0_1123
	s_add_i32 s12, s49, 0xfffff520
	s_mul_i32 s13, s12, 0xcccd
	s_lshr_b32 s38, s13, 23
	s_mul_i32 s13, s38, 0xffffff60
	s_add_i32 s13, s13, s12
	v_mov_b32_e32 v0, v195
	s_lshl_b32 s12, s13, 5
	s_ashr_i32 s13, s12, 31
	v_and_b32_e32 v8, 31, v0
	v_mov_b32_e32 v0, v195
	s_lshl_b32 s39, s38, 5
	s_lshl_b64 s[16:17], s[12:13], 2
	v_readlane_b32 s13, v253, 47
	s_add_u32 s16, s13, s16
	v_readlane_b32 s13, v253, 48
	v_ashrrev_i32_e32 v9, 5, v0
	s_addc_u32 s17, s13, s17
	v_lshlrev_b32_e32 v0, 2, v8
	v_lshl_add_u64 v[2:3], s[16:17], 0, v[0:1]
	v_add_u32_e32 v4, s39, v9
	s_movk_i32 s40, 0x5000
	v_mad_i64_i32 v[4:5], s[16:17], v4, s40, v[2:3]
	s_waitcnt lgkmcnt(0)
	s_barrier
	global_load_dword v80, v[4:5], off
	s_movk_i32 s13, 0x84
	v_mad_u64_u32 v[4:5], s[16:17], v9, s13, v[0:1]
	v_add_u32_e32 v10, 8, v9
	v_add_u32_e32 v5, s39, v10
	v_add_u32_e32 v11, 16, v9
	v_add_u32_e32 v12, 24, v9
	s_lshl_b32 s13, s38, 6
	v_mad_i64_i32 v[6:7], s[16:17], v5, s40, v[2:3]
	global_load_dword v81, v[6:7], off
	v_add_u32_e32 v5, s39, v11
	v_mad_i64_i32 v[6:7], s[16:17], v5, s40, v[2:3]
	global_load_dword v82, v[6:7], off
	v_add_u32_e32 v6, s12, v9
	v_add_u32_e32 v5, s39, v12
	v_mad_i64_i32 v[2:3], s[16:17], v5, s40, v[2:3]
	global_load_dword v83, v[2:3], off
	s_waitcnt vmcnt(3)
	ds_write_b32 v4, v80
	s_waitcnt vmcnt(2)
	ds_write_b32 v4, v81 offset:1056
	s_waitcnt vmcnt(1)
	ds_write_b32 v4, v82 offset:2112
	s_waitcnt vmcnt(0)
	ds_write_b32 v4, v83 offset:3168
	s_add_u32 s16, s28, s13
	s_addc_u32 s17, s29, 0
	s_movk_i32 s13, 0x880
	v_lshl_or_b32 v4, v8, 7, v0
	v_lshlrev_b32_e32 v0, 1, v8
	v_lshl_add_u64 v[2:3], s[16:17], 0, v[0:1]
	v_lshl_add_u32 v0, v9, 2, v4
	s_waitcnt lgkmcnt(0)
	s_barrier
	ds_read2_b32 v[4:5], v0 offset1:8
	v_mad_i64_i32 v[6:7], s[16:17], v6, s13, v[2:3]
	s_waitcnt lgkmcnt(0)
	v_cvt_pk_bf16_f32 v4, v4, s0
	global_store_short v[6:7], v4, off
	v_add_u32_e32 v4, s12, v10
	v_cvt_pk_bf16_f32 v6, v5, s0
	v_mad_i64_i32 v[4:5], s[16:17], v4, s13, v[2:3]
	global_store_short v[4:5], v6, off
	ds_read2_b32 v[4:5], v0 offset0:16 offset1:24
	s_waitcnt lgkmcnt(0)
	v_cvt_pk_bf16_f32 v0, v4, s0
	v_add_u32_e32 v4, s12, v11
	v_mad_i64_i32 v[6:7], s[16:17], v4, s13, v[2:3]
	v_add_u32_e32 v4, s12, v12
	global_store_short v[6:7], v0, off
	v_cvt_pk_bf16_f32 v0, v5, s0
	v_mad_i64_i32 v[2:3], s[12:13], v4, s13, v[2:3]
	global_store_short v[2:3], v0, off

; DEV int tidx() { int t = threadIdx.x; asm volatile("" : "+v"(t)); return t; }
; DEV void transpose_tile(const float* __restrict__ W, int K, int N, bf16_t* __restrict__ Wt, int ldt, int tile, char* smem) {
;   float* sm = (float*)smem;
;   const int ntn = N >> 5;
;   const int kt = tile / ntn, nt = tile - kt * ntn;
;   const int tx = tidx() & 31, ty = tidx() >> 5;
;   __syncthreads();
; #pragma unroll
;   for (int i = 0; i < 4; i++) { int k = ty + i * 8; sm[k * 33 + tx] = W[(size_t)(kt * 32 + k) * N + nt * 32 + tx]; }
;   __syncthreads();
; #pragma unroll
;   for (int i = 0; i < 4; i++) { int n = ty + i * 8; Wt[(size_t)(nt * 32 + n) * ldt + kt * 32 + tx] = f2bf(sm[tx * 33 + n]); }
; }
; DEV void phase_prep(const Params& p, char* smem) {
;     ...
;       if (it < NT_WOUT) { transpose_tile(p.in[I_WOUT], 1024, 1024, WSP(bf16_t, S_WOUT0), LDH, it, smem); continue; }
.LBB0_1124:
	s_andn2_b64 vcc, exec, s[12:13]
	s_cbranch_vccnz .LBB0_1126
	s_add_i32 s12, s49, 0xfffff920
	v_mov_b32_e32 v0, v195
	s_and_b32 s52, s12, 0xffffffe0
	s_lshl_b32 s12, s12, 5
	v_and_b32_e32 v8, 31, v0
	v_mov_b32_e32 v0, v195
	s_and_b32 s12, s12, 0x3e0
	s_lshl_b32 s13, s12, 2
	v_ashrrev_i32_e32 v9, 5, v0
	v_readlane_b32 s16, v253, 45
	s_add_u32 s16, s16, s13
	v_readlane_b32 s13, v253, 46
	v_add_u32_e32 v4, s52, v9
	s_addc_u32 s17, s13, 0
	v_lshlrev_b32_e32 v0, 2, v8
	v_ashrrev_i32_e32 v5, 31, v4
	v_lshl_add_u64 v[2:3], s[16:17], 0, v[0:1]
	v_lshlrev_b64 v[4:5], 12, v[4:5]
	v_lshl_add_u64 v[4:5], v[2:3], 0, v[4:5]
	s_waitcnt lgkmcnt(0)
	s_barrier
	global_load_dword v80, v[4:5], off
	s_movk_i32 s13, 0x84
	v_mad_u64_u32 v[4:5], s[16:17], v9, s13, v[0:1]
	v_add_u32_e32 v10, 8, v9
	v_add_u32_e32 v11, 16, v9
	v_add_u32_e32 v12, 24, v9
	s_lshl_b64 s[16:17], s[52:53], 1
	s_add_u32 s16, s30, s16
	s_addc_u32 s17, s31, s17
	s_movk_i32 s13, 0x880
	v_add_u32_e32 v6, s52, v10
	v_ashrrev_i32_e32 v7, 31, v6
	v_lshlrev_b64 v[6:7], 12, v[6:7]
	v_lshl_add_u64 v[6:7], v[2:3], 0, v[6:7]
	global_load_dword v81, v[6:7], off
	v_add_u32_e32 v6, s52, v11
	v_ashrrev_i32_e32 v7, 31, v6
	v_lshlrev_b64 v[6:7], 12, v[6:7]
	v_lshl_add_u64 v[6:7], v[2:3], 0, v[6:7]
	global_load_dword v82, v[6:7], off
	v_add_u32_e32 v6, s52, v12
	v_ashrrev_i32_e32 v7, 31, v6
	v_lshlrev_b64 v[6:7], 12, v[6:7]
	v_lshl_add_u64 v[2:3], v[2:3], 0, v[6:7]
	global_load_dword v83, v[2:3], off
	s_waitcnt vmcnt(3)
	ds_write_b32 v4, v80
	s_waitcnt vmcnt(2)
	ds_write_b32 v4, v81 offset:1056
	s_waitcnt vmcnt(1)
	ds_write_b32 v4, v82 offset:2112
	s_waitcnt vmcnt(0)
	ds_write_b32 v4, v83 offset:3168
	v_add_u32_e32 v6, s12, v9
	v_lshl_or_b32 v4, v8, 7, v0
	v_lshlrev_b32_e32 v0, 1, v8
	v_lshl_add_u64 v[2:3], s[16:17], 0, v[0:1]
	v_lshl_add_u32 v0, v9, 2, v4
	s_waitcnt lgkmcnt(0)
	s_barrier
	ds_read2_b32 v[4:5], v0 offset1:8
	v_mad_i64_i32 v[6:7], s[16:17], v6, s13, v[2:3]
	s_waitcnt lgkmcnt(0)
	v_cvt_pk_bf16_f32 v4, v4, s0
	global_store_short v[6:7], v4, off
	v_add_u32_e32 v4, s12, v10
	v_cvt_pk_bf16_f32 v6, v5, s0
	v_mad_i64_i32 v[4:5], s[16:17], v4, s13, v[2:3]
	global_store_short v[4:5], v6, off
	ds_read2_b32 v[4:5], v0 offset0:16 offset1:24
	s_waitcnt lgkmcnt(0)
	v_cvt_pk_bf16_f32 v0, v4, s0
	v_add_u32_e32 v4, s12, v11
	v_mad_i64_i32 v[6:7], s[16:17], v4, s13, v[2:3]
	v_add_u32_e32 v4, s12, v12
	global_store_short v[6:7], v0, off
	v_cvt_pk_bf16_f32 v0, v5, s0
	v_mad_i64_i32 v[2:3], s[12:13], v4, s13, v[2:3]
	global_store_short v[2:3], v0, off

; DEV int tidx() { int t = threadIdx.x; asm volatile("" : "+v"(t)); return t; }
; DEV void transpose_tile(const float* __restrict__ W, int K, int N, bf16_t* __restrict__ Wt, int ldt, int tile, char* smem) {
;   float* sm = (float*)smem;
;   const int ntn = N >> 5;
;   const int kt = tile / ntn, nt = tile - kt * ntn;
;   const int tx = tidx() & 31, ty = tidx() >> 5;
;   __syncthreads();
; #pragma unroll
;   for (int i = 0; i < 4; i++) { int k = ty + i * 8; sm[k * 33 + tx] = W[(size_t)(kt * 32 + k) * N + nt * 32 + tx]; }
;   __syncthreads();
; #pragma unroll
;   for (int i = 0; i < 4; i++) { int n = ty + i * 8; Wt[(size_t)(nt * 32 + n) * ldt + kt * 32 + tx] = f2bf(sm[tx * 33 + n]); }
; }
; DEV void phase_prep(const Params& p, char* smem) {
;     ...
;       if (it < NT_WUKV) { transpose_tile(p.in[I_WUKV], 128, 1024, WSP(bf16_t, S_WUKV), 128, it, smem); continue; }
.LBB0_1127:
	s_andn2_b64 vcc, exec, s[12:13]
	s_cbranch_vccnz .LBB0_1129
	s_add_i32 s12, s49, 0xfffff9a0
	v_mov_b32_e32 v0, v195
	s_and_b32 s52, s12, 0xffffffe0
	s_lshl_b32 s12, s12, 5
	v_and_b32_e32 v8, 31, v0
	v_mov_b32_e32 v0, v195
	s_and_b32 s12, s12, 0x3e0
	s_lshl_b32 s13, s12, 2
	v_ashrrev_i32_e32 v9, 5, v0
	v_readlane_b32 s16, v253, 35
	s_add_u32 s16, s16, s13
	v_readlane_b32 s13, v253, 36
	v_add_u32_e32 v4, s52, v9
	s_addc_u32 s17, s13, 0
	v_lshlrev_b32_e32 v0, 2, v8
	v_ashrrev_i32_e32 v5, 31, v4
	v_lshl_add_u64 v[2:3], s[16:17], 0, v[0:1]
	v_lshlrev_b64 v[4:5], 12, v[4:5]
	v_lshl_add_u64 v[4:5], v[2:3], 0, v[4:5]
	s_waitcnt lgkmcnt(0)
	s_barrier
	global_load_dword v80, v[4:5], off
	s_movk_i32 s13, 0x84
	v_mad_u64_u32 v[4:5], s[16:17], v9, s13, v[0:1]
	v_add_u32_e32 v10, 8, v9
	v_add_u32_e32 v11, 16, v9
	v_add_u32_e32 v12, 24, v9
	s_lshl_b64 s[16:17], s[52:53], 1
	s_add_u32 s16, s34, s16
	s_addc_u32 s17, s35, s17
	v_add_u32_e32 v6, s52, v10
	v_ashrrev_i32_e32 v7, 31, v6
	v_lshlrev_b64 v[6:7], 12, v[6:7]
	v_lshl_add_u64 v[6:7], v[2:3], 0, v[6:7]
	global_load_dword v81, v[6:7], off
	v_add_u32_e32 v6, s52, v11
	v_ashrrev_i32_e32 v7, 31, v6
	v_lshlrev_b64 v[6:7], 12, v[6:7]
	v_lshl_add_u64 v[6:7], v[2:3], 0, v[6:7]
	global_load_dword v82, v[6:7], off
	v_add_u32_e32 v6, s52, v12
	v_ashrrev_i32_e32 v7, 31, v6
	v_lshlrev_b64 v[6:7], 12, v[6:7]
	v_lshl_add_u64 v[2:3], v[2:3], 0, v[6:7]
	global_load_dword v83, v[2:3], off
	s_waitcnt vmcnt(3)
	ds_write_b32 v4, v80
	s_waitcnt vmcnt(2)
	ds_write_b32 v4, v81 offset:1056
	s_waitcnt vmcnt(1)
	ds_write_b32 v4, v82 offset:2112
	s_waitcnt vmcnt(0)
	ds_write_b32 v4, v83 offset:3168
	v_add_u32_e32 v6, s12, v9
	v_ashrrev_i32_e32 v7, 31, v6
	v_lshlrev_b64 v[6:7], 8, v[6:7]
	v_lshl_or_b32 v4, v8, 7, v0
	v_lshlrev_b32_e32 v0, 1, v8
	v_lshl_add_u64 v[2:3], s[16:17], 0, v[0:1]
	v_lshl_add_u32 v0, v9, 2, v4
	s_waitcnt lgkmcnt(0)
	s_barrier
	ds_read2_b32 v[4:5], v0 offset1:8
	v_lshl_add_u64 v[6:7], v[2:3], 0, v[6:7]
	s_waitcnt lgkmcnt(0)
	v_cvt_pk_bf16_f32 v4, v4, s0
	global_store_short v[6:7], v4, off
	v_add_u32_e32 v4, s12, v10
	v_cvt_pk_bf16_f32 v6, v5, s0
	v_ashrrev_i32_e32 v5, 31, v4
	v_lshlrev_b64 v[4:5], 8, v[4:5]
	v_lshl_add_u64 v[4:5], v[2:3], 0, v[4:5]
	global_store_short v[4:5], v6, off
	ds_read2_b32 v[4:5], v0 offset0:16 offset1:24
	v_add_u32_e32 v6, s12, v11
	v_ashrrev_i32_e32 v7, 31, v6
	v_lshlrev_b64 v[6:7], 8, v[6:7]
	v_lshl_add_u64 v[6:7], v[2:3], 0, v[6:7]
	s_waitcnt lgkmcnt(0)
	v_cvt_pk_bf16_f32 v0, v4, s0
	v_add_u32_e32 v4, s12, v12
	global_store_short v[6:7], v0, off
	v_cvt_pk_bf16_f32 v0, v5, s0
	v_ashrrev_i32_e32 v5, 31, v4
	v_lshlrev_b64 v[4:5], 8, v[4:5]
	v_lshl_add_u64 v[2:3], v[2:3], 0, v[4:5]
	global_store_short v[2:3], v0, off

; DEV int tidx() { int t = threadIdx.x; asm volatile("" : "+v"(t)); return t; }
; DEV void transpose_tile(const float* __restrict__ W, int K, int N, bf16_t* __restrict__ Wt, int ldt, int tile, char* smem) {
;   float* sm = (float*)smem;
;   const int ntn = N >> 5;
;   const int kt = tile / ntn, nt = tile - kt * ntn;
;   const int tx = tidx() & 31, ty = tidx() >> 5;
;   __syncthreads();
; #pragma unroll
;   for (int i = 0; i < 4; i++) { int k = ty + i * 8; sm[k * 33 + tx] = W[(size_t)(kt * 32 + k) * N + nt * 32 + tx]; }
;   __syncthreads();
; #pragma unroll
;   for (int i = 0; i < 4; i++) { int n = ty + i * 8; Wt[(size_t)(nt * 32 + n) * ldt + kt * 32 + tx] = f2bf(sm[tx * 33 + n]); }
; }
; DEV void phase_prep(const Params& p, char* smem) {
;     ...
;       if (it < NT_WUQ) { transpose_tile(p.in[I_WUQ], 256, 768, WSP(bf16_t, S_WUQ), 256, it, smem); continue; }
.LBB0_1130:
	s_andn2_b64 vcc, exec, s[12:13]
	s_cbranch_vccnz .LBB0_1132
	s_add_i32 s12, s49, 0xfffffa60
	s_mul_i32 s13, s12, 0xab
	s_bfe_u32 s38, s13, 0x4000c
	s_mul_i32 s13, s38, 0xffffffe8
	s_add_i32 s13, s13, s12
	v_mov_b32_e32 v0, v195
	s_lshl_b32 s12, s13, 5
	s_ashr_i32 s13, s12, 31
	v_and_b32_e32 v8, 31, v0
	v_mov_b32_e32 v0, v195
	s_lshl_b32 s39, s38, 5
	s_lshl_b64 s[16:17], s[12:13], 2
	v_readlane_b32 s13, v253, 31
	s_add_u32 s16, s13, s16
	v_readlane_b32 s13, v253, 32
	v_ashrrev_i32_e32 v9, 5, v0
	s_addc_u32 s17, s13, s17
	v_lshlrev_b32_e32 v0, 2, v8
	v_lshl_add_u64 v[2:3], s[16:17], 0, v[0:1]
	v_add_u32_e32 v4, s39, v9
	s_movk_i32 s13, 0xc00
	v_mad_i64_i32 v[4:5], s[16:17], v4, s13, v[2:3]
	s_waitcnt lgkmcnt(0)
	s_barrier
	global_load_dword v80, v[4:5], off
	s_movk_i32 s16, 0x84
	v_mad_u64_u32 v[4:5], s[16:17], v9, s16, v[0:1]
	v_add_u32_e32 v10, 8, v9
	v_add_u32_e32 v5, s39, v10
	v_add_u32_e32 v11, 16, v9
	v_add_u32_e32 v12, 24, v9
	v_mad_i64_i32 v[6:7], s[16:17], v5, s13, v[2:3]
	global_load_dword v81, v[6:7], off
	v_add_u32_e32 v5, s39, v11
	v_mad_i64_i32 v[6:7], s[16:17], v5, s13, v[2:3]
	global_load_dword v82, v[6:7], off
	v_add_u32_e32 v6, s12, v9
	v_ashrrev_i32_e32 v7, 31, v6
	v_lshlrev_b64 v[6:7], 9, v[6:7]
	v_add_u32_e32 v5, s39, v12
	v_mad_i64_i32 v[2:3], s[16:17], v5, s13, v[2:3]
	global_load_dword v83, v[2:3], off
	s_waitcnt vmcnt(3)
	ds_write_b32 v4, v80
	s_waitcnt vmcnt(2)
	ds_write_b32 v4, v81 offset:1056
	s_waitcnt vmcnt(1)
	ds_write_b32 v4, v82 offset:2112
	s_waitcnt vmcnt(0)
	ds_write_b32 v4, v83 offset:3168
	s_lshl_b32 s13, s38, 6
	s_add_u32 s16, s36, s13
	s_addc_u32 s17, s37, 0
	v_lshl_or_b32 v4, v8, 7, v0
	v_lshlrev_b32_e32 v0, 1, v8
	v_lshl_add_u64 v[2:3], s[16:17], 0, v[0:1]
	v_lshl_add_u32 v0, v9, 2, v4
	s_waitcnt lgkmcnt(0)
	s_barrier
	ds_read2_b32 v[4:5], v0 offset1:8
	v_lshl_add_u64 v[6:7], v[2:3], 0, v[6:7]
	s_waitcnt lgkmcnt(0)
	v_cvt_pk_bf16_f32 v4, v4, s0
	global_store_short v[6:7], v4, off
	v_add_u32_e32 v4, s12, v10
	v_cvt_pk_bf16_f32 v6, v5, s0
	v_ashrrev_i32_e32 v5, 31, v4
	v_lshlrev_b64 v[4:5], 9, v[4:5]
	v_lshl_add_u64 v[4:5], v[2:3], 0, v[4:5]
	global_store_short v[4:5], v6, off
	ds_read2_b32 v[4:5], v0 offset0:16 offset1:24
	v_add_u32_e32 v6, s12, v11
	v_ashrrev_i32_e32 v7, 31, v6
	v_lshlrev_b64 v[6:7], 9, v[6:7]
	v_lshl_add_u64 v[6:7], v[2:3], 0, v[6:7]
	s_waitcnt lgkmcnt(0)
	v_cvt_pk_bf16_f32 v0, v4, s0
	v_add_u32_e32 v4, s12, v12
	global_store_short v[6:7], v0, off
	v_cvt_pk_bf16_f32 v0, v5, s0
	v_ashrrev_i32_e32 v5, 31, v4
	v_lshlrev_b64 v[4:5], 9, v[4:5]
	v_lshl_add_u64 v[2:3], v[2:3], 0, v[4:5]
	global_store_short v[2:3], v0, off

; DEV int tidx() { int t = threadIdx.x; asm volatile("" : "+v"(t)); return t; }
; DEV void transpose_tile(const float* __restrict__ W, int K, int N, bf16_t* __restrict__ Wt, int ldt, int tile, char* smem) {
;   float* sm = (float*)smem;
;   const int ntn = N >> 5;
;   const int kt = tile / ntn, nt = tile - kt * ntn;
;   const int tx = tidx() & 31, ty = tidx() >> 5;
;   __syncthreads();
; #pragma unroll
;   for (int i = 0; i < 4; i++) { int k = ty + i * 8; sm[k * 33 + tx] = W[(size_t)(kt * 32 + k) * N + nt * 32 + tx]; }
;   __syncthreads();
; #pragma unroll
;   for (int i = 0; i < 4; i++) { int n = ty + i * 8; Wt[(size_t)(nt * 32 + n) * ldt + kt * 32 + tx] = f2bf(sm[tx * 33 + n]); }
; }
; DEV void phase_prep(const Params& p, char* smem) {
;     ...
;       if (it < NT_WIN) { transpose_tile(p.in[I_WIN], 1024, 1440, WSP(bf16_t, S_WIN0), LDH, it, smem); continue; }
.LBB0_1133:
	s_andn2_b64 vcc, exec, s[12:13]
	s_cbranch_vccnz .LBB0_1065
	s_mul_hi_i32 s12, s49, 0xb60b60b7
	s_add_i32 s12, s12, s49
	s_lshr_b32 s13, s12, 31
	s_ashr_i32 s12, s12, 5
	s_add_i32 s12, s12, s13
	s_mul_i32 s13, s12, 0xffffffd3
	s_add_i32 s13, s13, s49
	v_mov_b32_e32 v0, v195
	s_lshl_b32 s16, s12, 5
	s_lshl_b32 s12, s13, 5
	s_ashr_i32 s13, s12, 31
	v_and_b32_e32 v8, 31, v0
	v_mov_b32_e32 v0, v195
	s_lshl_b64 s[38:39], s[12:13], 2
	v_readlane_b32 s13, v253, 27
	s_add_u32 s38, s13, s38
	v_readlane_b32 s13, v253, 28
	v_ashrrev_i32_e32 v9, 5, v0
	s_addc_u32 s39, s13, s39
	v_lshlrev_b32_e32 v0, 2, v8
	v_lshl_add_u64 v[2:3], s[38:39], 0, v[0:1]
	v_add_u32_e32 v4, s16, v9
	s_movk_i32 s17, 0x1680
	v_mad_i64_i32 v[4:5], s[38:39], v4, s17, v[2:3]
	s_waitcnt lgkmcnt(0)
	s_barrier
	global_load_dword v80, v[4:5], off
	s_movk_i32 s13, 0x84
	v_mad_u64_u32 v[4:5], s[38:39], v9, s13, v[0:1]
	v_add_u32_e32 v10, 8, v9
	v_add_u32_e32 v5, s16, v10
	v_add_u32_e32 v11, 16, v9
	v_add_u32_e32 v12, 24, v9
	s_movk_i32 s13, 0x880
	v_mad_i64_i32 v[6:7], s[38:39], v5, s17, v[2:3]
	global_load_dword v81, v[6:7], off
	v_add_u32_e32 v5, s16, v11
	v_mad_i64_i32 v[6:7], s[38:39], v5, s17, v[2:3]
	global_load_dword v82, v[6:7], off
	v_add_u32_e32 v6, s12, v9
	v_add_u32_e32 v5, s16, v12
	v_mad_i64_i32 v[2:3], s[38:39], v5, s17, v[2:3]
	global_load_dword v83, v[2:3], off
	s_waitcnt vmcnt(3)
	ds_write_b32 v4, v80
	s_waitcnt vmcnt(2)
	ds_write_b32 v4, v81 offset:1056
	s_waitcnt vmcnt(1)
	ds_write_b32 v4, v82 offset:2112
	s_waitcnt vmcnt(0)
	ds_write_b32 v4, v83 offset:3168
	s_ashr_i32 s17, s16, 31
	s_lshl_b64 s[16:17], s[16:17], 1
	s_add_u32 s16, s46, s16
	s_addc_u32 s17, s47, s17
	v_lshl_or_b32 v4, v8, 7, v0
	v_lshlrev_b32_e32 v0, 1, v8
	v_lshl_add_u64 v[2:3], s[16:17], 0, v[0:1]
	v_lshl_add_u32 v0, v9, 2, v4
	s_waitcnt lgkmcnt(0)
	s_barrier
	ds_read2_b32 v[4:5], v0 offset1:8
	v_mad_i64_i32 v[6:7], s[16:17], v6, s13, v[2:3]
	s_waitcnt lgkmcnt(0)
	v_cvt_pk_bf16_f32 v4, v4, s0
	global_store_short v[6:7], v4, off
	v_add_u32_e32 v4, s12, v10
	v_cvt_pk_bf16_f32 v6, v5, s0
	v_mad_i64_i32 v[4:5], s[16:17], v4, s13, v[2:3]
	global_store_short v[4:5], v6, off
	ds_read2_b32 v[4:5], v0 offset0:16 offset1:24
	s_waitcnt lgkmcnt(0)
	v_cvt_pk_bf16_f32 v0, v4, s0
	v_add_u32_e32 v4, s12, v11
	v_mad_i64_i32 v[6:7], s[16:17], v4, s13, v[2:3]
	v_add_u32_e32 v4, s12, v12
	global_store_short v[6:7], v0, off
	v_cvt_pk_bf16_f32 v0, v5, s0
	v_mad_i64_i32 v[2:3], s[12:13], v4, s13, v[2:3]
	global_store_short v[2:3], v0, off
	s_branch .LBB0_1065
